# grid barrier: member workgroups poll the global generation flag directly (flat release, hierarchical arrival), own buffer_inv sc1 kept
# speedup vs baseline: 1.0082x; 1.0082x over previous
; __device__ __forceinline__ unsigned xb_ld(unsigned* p)              { return __hip_atomic_load(p, __ATOMIC_RELAXED, __HIP_MEMORY_SCOPE_AGENT); }
; __device__ __forceinline__ unsigned xb_add(unsigned* p, unsigned v) { return __hip_atomic_fetch_add(p, v, __ATOMIC_RELAXED, __HIP_MEMORY_SCOPE_AGENT); }
; #define XB_SPIN(cond, bar) do { unsigned _sp = 0; while (cond) { __builtin_amdgcn_s_sleep(1); \
;     if ((++_sp & 255u) == 0u) { if (xb_ld(&(bar)[XB_TMO])) break; if (_sp > XB_SPIN_CAP) { atomicAdd(&(bar)[XB_TMO], 1u); break; } } } } while (0)
; __device__ __forceinline__ void xcd_barrier(const XcdBarrier& b, const bool xb_is_leader) {
;     ...
;         const unsigned old = xb_add(&bar[XB_XSUB(b.x)], 1u);
;         const unsigned gen = old / nloc;
;         if (old + 1u == (gen + 1u) * nloc) {
;             __builtin_amdgcn_fence(__ATOMIC_RELEASE, "agent");
;             asm volatile("s_waitcnt vmcnt(0)" ::: "memory");
;             const unsigned og = xb_add(&bar[XB_TOP], 1u);
;             const unsigned tg = og / nx;
;             if (og + 1u == (tg + 1u) * nx) xb_add(&bar[XB_TOPGEN], 1u);
;             else XB_SPIN(xb_ld(&bar[XB_TOPGEN]) == tg, bar);
;             __builtin_amdgcn_fence(__ATOMIC_ACQUIRE, "agent");
;             xb_add(&bar[XB_XGEN(b.x)], 1u);
;             asm volatile("s_waitcnt vmcnt(0)" ::: "memory");
;         } else {
;             XB_SPIN(xb_ld(&bar[XB_XGEN(b.x)]) == gen, bar);
.LBB0_204:
	s_or_b64 exec, exec, s[8:9]
	v_cvt_f32_u32_e32 v4, v2
	s_waitcnt vmcnt(0)
	v_readfirstlane_b32 s0, v3
	v_sub_u32_e32 v3, 0, v2
	v_rcp_iflag_f32_e32 v4, v4
	v_add_u32_e32 v5, s0, v1
	v_mul_f32_e32 v4, 0x4f7ffffe, v4
	v_cvt_u32_f32_e32 v4, v4
	v_mul_lo_u32 v1, v3, v4
	v_mul_hi_u32 v1, v4, v1
	v_add_u32_e32 v1, v4, v1
	v_mul_hi_u32 v1, v5, v1
	v_mul_lo_u32 v3, v1, v2
	v_sub_u32_e32 v3, v5, v3
	v_add_u32_e32 v4, 1, v1
	v_cmp_ge_u32_e32 vcc, v3, v2
	s_nop 1
	v_cndmask_b32_e32 v1, v1, v4, vcc
	v_sub_u32_e32 v4, v3, v2
	v_cndmask_b32_e32 v3, v3, v4, vcc
	v_add_u32_e32 v4, 1, v1
	v_cmp_ge_u32_e32 vcc, v3, v2
	v_add_u32_e32 v3, 1, v5
	s_nop 0
	v_cndmask_b32_e32 v1, v1, v4, vcc
	v_mul_lo_u32 v4, v2, v1
	v_add_u32_e32 v2, v4, v2
	v_cmp_ne_u32_e32 vcc, v3, v2
	s_and_saveexec_b64 s[0:1], vcc
	s_xor_b64 s[0:1], exec, s[0:1]
	s_cbranch_execz .LBB0_218
	s_waitcnt lgkmcnt(0)
	v_mov_b32_e32 v0, 0x3500
	global_load_dword v0, v0, s[76:77] sc1
	s_add_u32 s10, s76, 0x3500
	s_addc_u32 s11, s77, 0
	s_waitcnt vmcnt(0)
	v_cmp_eq_u32_e32 vcc, v0, v1
	s_and_saveexec_b64 s[8:9], vcc
	s_cbranch_execz .LBB0_217
	s_mov_b32 s2, 1
	s_mov_b64 s[12:13], 0
	v_mov_b32_e32 v0, 0
	s_branch .LBB0_208
